# attention: waves 4-7 staggered half a tile step (their per-step barrier sits mid-body after their K/V LDS writes), waves 0-3 unchanged
# speedup vs baseline: 1.0129x; 1.0129x over previous
; #define LAS __attribute__((address_space(3)))
; __device__ __forceinline__ int mk_tid(int wid_s) { return wid_s * 64 + lane_id(); }
; template <int MODE>
; __device__ __forceinline__ void attn_phase(const Args& a, bool do_ctx, LAS unsigned char* lds, const int wid_s) {
;     const int tid = mk_tid(wid_s);
;     const int lane = tid & 63, wid = wid_s, ql = lane & 31, hf = lane >> 5, G = gridDim.x;
;     const bf16_t* Q = (const bf16_t*)(a.ws + WS_Q); const bf16_t* KN = (const bf16_t*)(a.ws + WS_KN); const bf16_t* KR = (const bf16_t*)(a.ws + WS_KR);
;     const bf16_t* VT = (const bf16_t*)(a.ws + WS_VT); bf16_t* AC = (bf16_t*)(a.ws + WS_AC);
;     const int nitems = 1024 + (do_ctx ? 32 : 0);
;     LAS unsigned char* const ldsv = lds + 2 * KBUF;
;     for (int it = 0;; ++it) {
;         const long L = (long)it * G + blockIdx.x; if (L >= nitems) break;
;         int b, h, qt, nkt;
;         if (L < 1024) { const int x = (int)(L % 8), q = (int)((L / 8) % 32), bh = (int)(L / 256) * 8 + x; b = bh >> 3; h = bh & 7; qt = q + 1; nkt = RPB / 64; }
;         else { const int bh = (int)(L - 1024); b = bh >> 3; h = bh & 7; qt = 0; nkt = CTXL / 64; }
;         const int rowbase = b * RPB;
;         const int qrow = rowbase + qt * 256 + wid * 32 + ql;
;         bf16x8 qf[6];
; #pragma unroll
;         for (int s = 0; s < 6; ++s) qf[s] = *(const bf16x8*)(Q + (size_t)qrow * 768 + h * 96 + s * 16 + hf * 8);
;         const bf16_t* gkn = KN + ((size_t)(rowbase + (tid >> 3))) * 512 + h * 64 + (tid & 7) * 8;
;         const bf16_t* gkr = KR + ((size_t)(rowbase + ((tid & 255) >> 2))) * 32 + (tid & 3) * 8;
;         const bf16_t* gvt = VT + ((size_t)((b * NH + h) * 64 + (tid >> 3))) * RPB + (tid & 7) * 8;
;         const unsigned skn = (unsigned)((tid >> 3) * KROW + (tid & 7) * 16);
;         const unsigned skr = (unsigned)(((tid & 255) >> 2) * KROW + 128 + (tid & 3) * 16);
;         const unsigned svt = (unsigned)((tid >> 3) * VROW + (tid & 7) * 16);
.LBB0_420:
	s_barrier
	v_mbcnt_lo_u32_b32 v1, -1, 0
	v_mbcnt_hi_u32_b32 v1, -1, v1
	v_readlane_b32 s0, v249, 8
	v_and_b32_e32 v5, 31, v1
	v_readlane_b32 s2, v249, 38
	v_add_u32_e32 v3, s0, v1
	s_cmp_ge_u32 s0, 0x100
	s_cselect_b32 s96, 1, 0
	v_and_b32_e32 v4, 63, v1
	v_bfe_u32 v6, v1, 5, 1
	v_or_b32_e32 v158, s2, v5
	v_and_b32_e32 v7, 7, v1
	v_lshlrev_b32_e32 v1, 4, v1
	v_readlane_b32 s2, v249, 50
	v_and_b32_e32 v132, 48, v1
	v_mov_b32_e32 v133, v201
	v_readlane_b32 s3, v249, 51
	v_readlane_b32 s0, v250, 5
	v_lshlrev_b32_e32 v136, 4, v7
	v_lshl_add_u64 v[134:135], s[2:3], 0, v[132:133]
	v_readlane_b32 s2, v249, 58
	v_mov_b32_e32 v137, v201
	v_readlane_b32 s3, v249, 59
	v_readlane_b32 s1, v250, 6
	v_ashrrev_i32_e32 v159, 3, v3
	v_lshl_add_u64 v[138:139], s[2:3], 0, v[136:137]
	s_movk_i32 s3, 0xd0
	s_movk_i32 s2, 0xffb8
	s_and_b64 s[0:1], s[0:1], exec
	v_lshlrev_b32_e32 v0, 3, v6
	v_bfe_u32 v160, v3, 2, 6
	v_mul_lo_u32 v1, v159, s3
	v_mul_lo_u32 v161, v159, s2
	s_movk_i32 s2, 0x100
	v_lshlrev_b32_e32 v4, 2, v4
	s_movk_i32 s0, 0x420
	s_mov_b32 s1, 0
	v_lshlrev_b32_e32 v2, 3, v7
	v_add3_u32 v162, v1, v136, 0
	v_cmp_gt_i32_e64 s[6:7], s2, v3
	v_mad_u32_u24 v1, v160, s3, v132
	v_mad_u32_u24 v3, v5, s3, 0
	v_and_b32_e32 v251, 6, v7
	v_lshlrev_b32_e32 v251, 4, v251
	v_and_b32_e32 v240, 1, v7
	v_lshl_add_u32 v251, v240, 3, v251
	s_movk_i32 s86, 0x90
	v_mad_u32_u24 v251, v159, s86, v251
	v_add_u32_e32 v251, 0x8c00, v251
	v_lshlrev_b32_e32 v7, 4, v6
	v_xor_b32_e32 v163, 0x80, v4
	v_add_u32_e32 v8, 0, v0
	v_mul_u32_u24_e32 v240, 0x90, v5
	v_lshl_add_u32 v240, v6, 4, v240
	v_mul_u32_u24_e32 v5, 0x88, v5
	v_lshlrev_b32_e32 v4, 2, v6
	s_cselect_b32 s0, s0, 0x400
	v_lshlrev_b32_e32 v200, 1, v0
	v_lshlrev_b32_e32 v140, 1, v2
	v_lshlrev_b32_e32 v142, 1, v4
	v_add_u32_e32 v164, 0, v1
	v_add_u32_e32 v165, v3, v7
	v_add_u32_e32 v166, v8, v5
	s_mov_b32 s24, s1
	s_branch .LBB0_423

; #define LAS __attribute__((address_space(3)))
; __device__ __forceinline__ float max3f(float a, float b, float c) { float d; asm("v_max3_f32 %0, %1, %2, %3" : "=v"(d) : "v"(a), "v"(b), "v"(c)); return d; }
; template <int MODE>
; __device__ __forceinline__ void attn_qk(const LAS unsigned char* kb_, const bf16x8 (&qf)[6], f32x16 (&st)[2], const int ql, const int hf) {
;     ...
;     bf16x8 ka[4], kc[4], ke[4];
; #pragma unroll
;     for (int s = 0; s < 2; ++s) { ka[2 * s] = ATT_KF(0, s); ka[2 * s + 1] = ATT_KF(1, s); }
; #pragma unroll
;     for (int s = 2; s < 4; ++s) { kc[2 * (s - 2)] = ATT_KF(0, s); kc[2 * (s - 2) + 1] = ATT_KF(1, s); }
; template <int MODE>
; __device__ __forceinline__ void attn_pv(const LAS unsigned char* vb_, f32x16 (&st)[2], f32x16 (&ot)[2], float& mrun, float& lsum, const int ql, const int hf, const int lane) {
;     if (MODE != 1) {
;     float mx = max3f(st[0][0], st[1][0], st[0][1]), my = max3f(st[1][1], st[0][2], st[1][2]);
; #pragma unroll
;     for (int i = 3; i < 15; i += 2) { mx = max3f(mx, st[0][i], st[1][i]); my = max3f(my, st[0][i + 1], st[1][i + 1]); }
;     mx = max3f(mx, st[0][15], st[1][15]); mx = max3f(mx, my, my);
;     if (__builtin_amdgcn_ballot_w64(mx > mrun + 8.0f) != 0ull) {
.LBB0_437:
	global_load_dwordx4 v[128:131], v150, s[84:85] offset:128
	s_cmp_lg_u32 s96, 0
	s_cbranch_scc1 .LattB_e
	ds_read_b128 v[64:67], v165 offset:13312
	ds_read_b128 v[168:171], v165 offset:13344
	ds_read_b128 v[68:71], v165 offset:19968
	ds_read_b128 v[172:175], v165 offset:20000
	ds_read_b128 v[176:179], v165 offset:13376
	ds_read_b128 v[180:183], v165 offset:13408
	ds_read_b128 v[184:187], v165 offset:20032
	ds_read_b128 v[188:191], v165 offset:20064
	ds_read_b128 v[206:209], v240 offset:31232
	ds_read_b128 v[210:213], v240 offset:26624
	ds_read_b128 v[214:217], v240 offset:31264
	ds_read_b128 v[218:221], v240 offset:26656
	ds_read_b128 v[222:225], v240 offset:31296
	ds_read_b128 v[226:229], v240 offset:26688
	ds_read_b128 v[236:239], v240 offset:26720
	v_max3_f32 v156, v48, v32, v49
	v_max3_f32 v157, v33, v50, v34
	v_max3_f32 v156, v156, v51, v35
	v_max3_f32 v157, v157, v52, v36
	v_max3_f32 v156, v156, v53, v37
	v_max3_f32 v157, v157, v54, v38
	v_max3_f32 v156, v156, v55, v39
	v_max3_f32 v157, v157, v56, v40
	v_max3_f32 v156, v156, v57, v41
	v_max3_f32 v157, v157, v58, v42
	v_max3_f32 v156, v156, v59, v43
	v_max3_f32 v157, v157, v60, v44
	v_max3_f32 v156, v156, v61, v45
	v_max3_f32 v157, v157, v62, v46
	v_max3_f32 v156, v156, v63, v47
	v_max3_f32 v157, v156, v157, v157
	v_add_f32_e32 v156, 0x41000000, v143
	v_cmp_gt_f32_e32 vcc, v157, v156
	s_cbranch_vccnz .Latt_e_nors_resc

; #define ATT_LOADK(rk, rr, kt_) do { if (MODE == 3 && (kt_) > 1) break; rk = *(const u32x4*)(gkn + (size_t)(kt_) * 64 * 512); rr = *(const u32x4*)(gkr + (size_t)(kt_) * 64 * 32); } while (0)
; #define ATT_LOADV(rv, kt_) do { if (MODE == 3 && (kt_) > 1) break; rv = *(const u32x4*)(gvt + (size_t)(kt_) * 64); } while (0)
; template <int MODE>
; __device__ __forceinline__ void attn_phase(const Args& a, bool do_ctx, LAS unsigned char* lds, const int wid_s) {
;     ...
;             if (t + 3 < nkt) ATT_LOADK(kK, kR, t + 3);
;             if (t + 2 < nkt) ATT_LOADV(vV, t + 2);
;             if (t + 2 < nkt) attn_qk<MODE>(lds, qf, sa, ql, hf);
;             __builtin_amdgcn_sched_barrier(0);
;             attn_pv<MODE>(ldsv + VBUF, sb, ot, mrun, lsum, ql, hf, lane);
.Latt_otop:
	s_cbranch_scc1 .Latt_o_noK
	s_add_u32 s86, s80, 0x10000
	s_addc_u32 s87, s81, 0
	s_add_u32 s88, s82, 0x1000
	s_addc_u32 s89, s83, 0
	global_load_dwordx4 v[120:123], v146, s[86:87]
	global_load_dwordx4 v[124:127], v148, s[88:89]
.Latt_o_noK:
	s_and_b64 vcc, exec, s[8:9]
	s_cbranch_vccnz .Latt_o_tail
	global_load_dwordx4 v[128:131], v150, s[84:85] offset:256
	s_cmp_lg_u32 s96, 0
	s_cbranch_scc1 .LattB_o
	ds_read_b128 v[32:35], v165
	ds_read_b128 v[152:155], v165 offset:32
	ds_read_b128 v[36:39], v165 offset:6656
	ds_read_b128 v[206:209], v165 offset:6688
	ds_read_b128 v[210:213], v165 offset:64
	ds_read_b128 v[214:217], v165 offset:96
	ds_read_b128 v[218:221], v165 offset:6720
	ds_read_b128 v[222:225], v165 offset:6752
	ds_read_b128 v[176:179], v240 offset:35840
	ds_read_b128 v[180:183], v240 offset:40448
	ds_read_b128 v[184:187], v240 offset:35872
	ds_read_b128 v[188:191], v240 offset:40480
	ds_read_b128 v[192:195], v240 offset:35904
	ds_read_b128 v[196:199], v240 offset:40512
	ds_read_b128 v[172:175], v240 offset:35936
	v_max3_f32 v156, v80, v64, v81
	v_max3_f32 v157, v65, v82, v66
	v_max3_f32 v156, v156, v83, v67
	v_max3_f32 v157, v157, v84, v68
	v_max3_f32 v156, v156, v85, v69
	v_max3_f32 v157, v157, v86, v70
	v_max3_f32 v156, v156, v87, v71
	v_max3_f32 v157, v157, v88, v72
	v_max3_f32 v156, v156, v89, v73
	v_max3_f32 v157, v157, v90, v74
	v_max3_f32 v156, v156, v91, v75
	v_max3_f32 v157, v157, v92, v76
	v_max3_f32 v156, v156, v93, v77
	v_max3_f32 v157, v157, v94, v78
	v_max3_f32 v156, v156, v95, v79
	v_max3_f32 v157, v156, v157, v157
	v_add_f32_e32 v156, 0x41000000, v143
	v_cmp_gt_f32_e32 vcc, v157, v156
	s_cbranch_vccnz .Latt_o_nors_resc

; #define LAS __attribute__((address_space(3)))
; __device__ __forceinline__ float fexp2(float x) { return __builtin_amdgcn_exp2f(x); }
; template <int MODE>
; __device__ __forceinline__ void attn_pv(const LAS unsigned char* vb_, f32x16 (&st)[2], f32x16 (&ot)[2], float& mrun, float& lsum, const int ql, const int hf, const int lane) {
;     if (MODE != 1) {
;     float mx = max3f(st[0][0], st[1][0], st[0][1]), my = max3f(st[1][1], st[0][2], st[1][2]);
; #pragma unroll
;     for (int i = 3; i < 15; i += 2) { mx = max3f(mx, st[0][i], st[1][i]); my = max3f(my, st[0][i + 1], st[1][i + 1]); }
;     mx = max3f(mx, st[0][15], st[1][15]); mx = max3f(mx, my, my);
;     if (__builtin_amdgcn_ballot_w64(mx > mrun + 8.0f) != 0ull) {
;         mx = fmaxf(mx, shx32(mx, lane));
;         const float mnew = (mx > mrun + 8.0f) ? mx : mrun;
;         const float alpha = fexp2(mrun - mnew);
;         mrun = mnew; lsum *= alpha;
; #pragma unroll
;         for (int i = 0; i < 16; ++i) { ot[0][i] *= alpha; ot[1][i] *= alpha; }
;     }
;     float ps = 0.f;
; #pragma unroll
;     for (int kb = 0; kb < 2; ++kb)
; #pragma unroll
;         for (int i = 0; i < 16; ++i) { const float p = fexp2(st[kb][i] - mrun); st[kb][i] = p; ps += p; }
;     lsum += ps;
;     } else lsum += st[0][0];
; #pragma unroll
;     for (int kb = 0; kb < 2; ++kb)
; #pragma unroll
;         for (int sI = 0; sI < 2; ++sI) {
;             u32x4 pw = {pk_bf16(st[kb][8 * sI + 0], st[kb][8 * sI + 1]), pk_bf16(st[kb][8 * sI + 2], st[kb][8 * sI + 3]),
;                         pk_bf16(st[kb][8 * sI + 4], st[kb][8 * sI + 5]), pk_bf16(st[kb][8 * sI + 6], st[kb][8 * sI + 7])};
;             const bf16x8 pf = __builtin_bit_cast(bf16x8, pw);
; #pragma unroll
;             for (int db = 0; db < 2; ++db) {
;                 const LAS unsigned char* vp = vb_ + (db * 32 + ql) * VROW + (kb * 32 + 16 * sI + 4 * hf) * 2;
;                 const u32x2 v0 = *(const LAS u32x2*)vp, v1 = *(const LAS u32x2*)(vp + 16);
;                 u32x4 vw = {v0[0], v0[1], v1[0], v1[1]};
;                 ot[db] = att_mma<MODE>(__builtin_bit_cast(bf16x8, vw), pf, ot[db]);
;             }
;         }
; }
; template <int MODE>
; __device__ __forceinline__ void attn_phase(const Args& a, bool do_ctx, LAS unsigned char* lds, const int wid_s) {
;     ...
;             if (t + 2 < nkt) ATT_WRITEK(kK, kR, 0);
;             ATT_WRITEV(vV, 1);
.LattB_e:
	ds_read_b128 v[64:67], v165 offset:13312
	ds_read_b128 v[168:171], v165 offset:13344
	ds_read_b128 v[68:71], v165 offset:19968
	ds_read_b128 v[172:175], v165 offset:20000
	ds_read_b128 v[176:179], v165 offset:13376
	ds_read_b128 v[180:183], v165 offset:13408
	ds_read_b128 v[184:187], v165 offset:20032
	ds_read_b128 v[188:191], v165 offset:20064
	ds_read_b128 v[206:209], v240 offset:31232
	ds_read_b128 v[210:213], v240 offset:26624
	ds_read_b128 v[214:217], v240 offset:31264
	ds_read_b128 v[218:221], v240 offset:26656
	ds_read_b128 v[222:225], v240 offset:31296
	ds_read_b128 v[226:229], v240 offset:26688
	ds_read_b128 v[236:239], v240 offset:26720
	v_max3_f32 v156, v48, v32, v49
	v_max3_f32 v157, v33, v50, v34
	v_max3_f32 v156, v156, v51, v35
	v_max3_f32 v157, v157, v52, v36
	v_max3_f32 v156, v156, v53, v37
	v_max3_f32 v157, v157, v54, v38
	v_max3_f32 v156, v156, v55, v39
	v_max3_f32 v157, v157, v56, v40
	v_max3_f32 v156, v156, v57, v41
	v_max3_f32 v157, v157, v58, v42
	v_max3_f32 v156, v156, v59, v43
	v_max3_f32 v157, v157, v60, v44
	v_max3_f32 v156, v156, v61, v45
	v_max3_f32 v157, v157, v62, v46
	v_max3_f32 v156, v156, v63, v47
	v_max3_f32 v157, v156, v157, v157
	v_add_f32_e32 v156, 0x41000000, v143
	v_cmp_gt_f32_e32 vcc, v157, v156
	s_cbranch_vccnz .Latt_eB_nors_resc
.Latt_eB_nors:
	s_cmp_eq_u32 s90, 0
	s_cbranch_scc1 .Latt_eB_nors_gen
	v_exp_f32_e32 v48, v48
	v_exp_f32_e32 v49, v49
	v_exp_f32_e32 v50, v50
	v_exp_f32_e32 v51, v51
	v_exp_f32_e32 v52, v52
	v_exp_f32_e32 v53, v53
	v_exp_f32_e32 v54, v54
	v_exp_f32_e32 v55, v55
	s_waitcnt lgkmcnt(11)
	v_mfma_f32_32x32x16_bf16 v[80:95], v[64:67], v[112:115], 0
	v_cvt_pk_bf16_f32 v152, v48, v49
	v_cvt_pk_bf16_f32 v153, v50, v51
	v_cvt_pk_bf16_f32 v154, v52, v53
	v_cvt_pk_bf16_f32 v155, v54, v55
	v_mfma_f32_32x32x16_bf16 v[64:79], v[68:71], v[112:115], 0
	v_pk_add_f32 v[230:231], v[48:49], v[50:51]
	v_pk_add_f32 v[230:231], v[230:231], v[52:53]
	v_pk_add_f32 v[230:231], v[230:231], v[54:55]
	v_mfma_f32_32x32x16_bf16 v[80:95], v[168:171], v[96:99], v[80:95]
	v_mfma_f32_32x32x16_bf16 v[64:79], v[172:175], v[96:99], v[64:79]
	ds_read_b128 v[168:171], v165 offset:13440
	ds_read_b128 v[172:175], v165 offset:13472
	ds_read_b128 v[192:195], v165 offset:20096
	ds_read_b128 v[196:199], v165 offset:20128
	v_exp_f32_e32 v56, v56
	v_exp_f32_e32 v57, v57
	v_exp_f32_e32 v58, v58
	v_exp_f32_e32 v59, v59
	s_waitcnt lgkmcnt(11)
	v_mfma_f32_32x32x16_bf16 v[80:95], v[176:179], v[100:103], v[80:95]
	ds_read_b128 a[0:3], v240 offset:31328
	v_exp_f32_e32 v60, v60
	v_exp_f32_e32 v61, v61
	v_exp_f32_e32 v62, v62
	v_exp_f32_e32 v63, v63
	v_mfma_f32_32x32x16_bf16 v[64:79], v[184:187], v[100:103], v[64:79]
	v_mfma_f32_32x32x16_bf16 v[80:95], v[180:183], v[104:107], v[80:95]
	v_cvt_pk_bf16_f32 v48, v56, v57
	v_cvt_pk_bf16_f32 v49, v58, v59
	v_cvt_pk_bf16_f32 v50, v60, v61
	v_cvt_pk_bf16_f32 v51, v62, v63
	v_mfma_f32_32x32x16_bf16 v[64:79], v[188:191], v[104:107], v[64:79]
	s_waitcnt lgkmcnt(10)
	v_mfma_f32_32x32x16_bf16 v[16:31], v[206:209], v[152:155], v[16:31]
	v_pk_add_f32 v[230:231], v[230:231], v[56:57]
	v_pk_add_f32 v[230:231], v[230:231], v[58:59]
	v_pk_add_f32 v[230:231], v[230:231], v[60:61]
	v_pk_add_f32 v[230:231], v[230:231], v[62:63]
	v_mfma_f32_32x32x16_bf16 v[0:15], v[210:213], v[152:155], v[0:15]
	s_andn2_b64 vcc, exec, s[10:11]
	s_cbranch_vccnz .Latt_wskip_eB1
	s_waitcnt vmcnt(2)
	ds_write_b128 v162, v[120:123]
	s_and_saveexec_b64 s[2:3], s[6:7]
	s_cbranch_execz .Latt_wk_eB1
	s_waitcnt vmcnt(1)
	ds_write_b128 v164, v[124:127] offset:128

; template <int MODE>
; __device__ __forceinline__ void attn_pv(const LAS unsigned char* vb_, f32x16 (&st)[2], f32x16 (&ot)[2], float& mrun, float& lsum, const int ql, const int hf, const int lane) {
;     if (MODE != 1) {
;     float mx = max3f(st[0][0], st[1][0], st[0][1]), my = max3f(st[1][1], st[0][2], st[1][2]);
; #pragma unroll
;     for (int i = 3; i < 15; i += 2) { mx = max3f(mx, st[0][i], st[1][i]); my = max3f(my, st[0][i + 1], st[1][i + 1]); }
;     mx = max3f(mx, st[0][15], st[1][15]); mx = max3f(mx, my, my);
;     if (__builtin_amdgcn_ballot_w64(mx > mrun + 8.0f) != 0ull) {
;         mx = fmaxf(mx, shx32(mx, lane));
;         const float mnew = (mx > mrun + 8.0f) ? mx : mrun;
;         const float alpha = fexp2(mrun - mnew);
;         mrun = mnew; lsum *= alpha;
; #pragma unroll
;         for (int i = 0; i < 16; ++i) { ot[0][i] *= alpha; ot[1][i] *= alpha; }
;     }
;     float ps = 0.f;
; #pragma unroll
;     for (int kb = 0; kb < 2; ++kb)
; #pragma unroll
;         for (int i = 0; i < 16; ++i) { const float p = fexp2(st[kb][i] - mrun); st[kb][i] = p; ps += p; }
;     lsum += ps;
;     } else lsum += st[0][0];
; #pragma unroll
;     for (int kb = 0; kb < 2; ++kb)
; #pragma unroll
;         for (int sI = 0; sI < 2; ++sI) {
;             u32x4 pw = {pk_bf16(st[kb][8 * sI + 0], st[kb][8 * sI + 1]), pk_bf16(st[kb][8 * sI + 2], st[kb][8 * sI + 3]),
;                         pk_bf16(st[kb][8 * sI + 4], st[kb][8 * sI + 5]), pk_bf16(st[kb][8 * sI + 6], st[kb][8 * sI + 7])};
;             const bf16x8 pf = __builtin_bit_cast(bf16x8, pw);
; #pragma unroll
;             for (int db = 0; db < 2; ++db) {
;                 const LAS unsigned char* vp = vb_ + (db * 32 + ql) * VROW + (kb * 32 + 16 * sI + 4 * hf) * 2;
;                 const u32x2 v0 = *(const LAS u32x2*)vp, v1 = *(const LAS u32x2*)(vp + 16);
;                 u32x4 vw = {v0[0], v0[1], v1[0], v1[1]};
;                 ot[db] = att_mma<MODE>(__builtin_bit_cast(bf16x8, vw), pf, ot[db]);
;             }
;         }
; }
; template <int MODE>
; __device__ __forceinline__ void attn_phase(const Args& a, bool do_ctx, LAS unsigned char* lds, const int wid_s) {
;     ...
;             ATT_WRITEV(vV, 1);
;             __syncthreads();
;             if (t + 3 < nkt) ATT_LOADK(kK, kR, t + 3);
;             if (t + 2 < nkt) ATT_LOADV(vV, t + 2);
;             if (t + 2 < nkt) attn_qk<MODE>(lds, qf, sa, ql, hf);
.Latt_wskip_eB1:
	s_waitcnt vmcnt(0)
	ds_write2_b64 v251, v[128:129], v[130:131] offset1:2
	v_exp_f32_e32 v32, v32
	v_exp_f32_e32 v33, v33
	v_exp_f32_e32 v34, v34
	v_exp_f32_e32 v35, v35
	s_waitcnt lgkmcnt(0)
	s_barrier
	v_mfma_f32_32x32x16_bf16 v[80:95], v[168:171], v[108:111], v[80:95]
	v_exp_f32_e32 v36, v36
	v_exp_f32_e32 v37, v37
	v_exp_f32_e32 v38, v38
	v_exp_f32_e32 v39, v39
	v_mfma_f32_32x32x16_bf16 v[16:31], v[214:217], v[48:51], v[16:31]
	v_mfma_f32_32x32x16_bf16 v[0:15], v[218:221], v[48:51], v[0:15]
	v_cvt_pk_bf16_f32 v152, v32, v33
	v_cvt_pk_bf16_f32 v153, v34, v35
	v_cvt_pk_bf16_f32 v154, v36, v37
	v_cvt_pk_bf16_f32 v155, v38, v39
	v_mfma_f32_32x32x16_bf16 v[64:79], v[192:195], v[108:111], v[64:79]
	v_pk_add_f32 v[230:231], v[230:231], v[32:33]
	v_pk_add_f32 v[230:231], v[230:231], v[34:35]
	v_pk_add_f32 v[230:231], v[230:231], v[36:37]
	v_pk_add_f32 v[230:231], v[230:231], v[38:39]
	v_mfma_f32_32x32x16_bf16 v[80:95], v[172:175], v[116:119], v[80:95]
	v_mfma_f32_32x32x16_bf16 v[64:79], v[196:199], v[116:119], v[64:79]
	v_exp_f32_e32 v40, v40
	v_exp_f32_e32 v41, v41
	v_exp_f32_e32 v42, v42
	v_exp_f32_e32 v43, v43
	v_mfma_f32_32x32x16_bf16 v[16:31], v[222:225], v[152:155], v[16:31]
	v_exp_f32_e32 v44, v44
	v_exp_f32_e32 v45, v45
	v_exp_f32_e32 v46, v46
	v_exp_f32_e32 v47, v47
	v_mfma_f32_32x32x16_bf16 v[0:15], v[226:229], v[152:155], v[0:15]
	v_cvt_pk_bf16_f32 v48, v40, v41
	v_cvt_pk_bf16_f32 v49, v42, v43
	v_cvt_pk_bf16_f32 v50, v44, v45
	v_cvt_pk_bf16_f32 v51, v46, v47
	v_pk_add_f32 v[230:231], v[230:231], v[40:41]
	v_pk_add_f32 v[230:231], v[230:231], v[42:43]
	v_pk_add_f32 v[230:231], v[230:231], v[44:45]
	v_pk_add_f32 v[230:231], v[230:231], v[46:47]
	v_add_f32_e32 v230, v230, v231
	v_add_f32_e32 v167, v167, v230
	v_mfma_f32_32x32x16_bf16 v[0:15], v[236:239], v[48:51], v[0:15]
	v_mfma_f32_32x32x16_bf16 v[16:31], a[0:3], v[48:51], v[16:31]
.Latt_eB_nors_join:
	s_not_b64 s[8:9], s[10:11]
	s_cmp_lt_u32 s12, s25
	s_cselect_b64 s[10:11], -1, 0
	s_cmp_ge_u32 s12, s25
	s_branch .Latt_otop
.LattB_o:
	ds_read_b128 v[32:35], v165
	ds_read_b128 v[152:155], v165 offset:32
	ds_read_b128 v[36:39], v165 offset:6656
	ds_read_b128 v[206:209], v165 offset:6688
	ds_read_b128 v[210:213], v165 offset:64
	ds_read_b128 v[214:217], v165 offset:96
	ds_read_b128 v[218:221], v165 offset:6720
	ds_read_b128 v[222:225], v165 offset:6752
	ds_read_b128 v[176:179], v240 offset:35840
	ds_read_b128 v[180:183], v240 offset:40448
	ds_read_b128 v[184:187], v240 offset:35872
	ds_read_b128 v[188:191], v240 offset:40480
	ds_read_b128 v[192:195], v240 offset:35904
	ds_read_b128 v[196:199], v240 offset:40512
	ds_read_b128 v[172:175], v240 offset:35936
	v_max3_f32 v156, v80, v64, v81
	v_max3_f32 v157, v65, v82, v66
	v_max3_f32 v156, v156, v83, v67
	v_max3_f32 v157, v157, v84, v68
	v_max3_f32 v156, v156, v85, v69
	v_max3_f32 v157, v157, v86, v70
	v_max3_f32 v156, v156, v87, v71
	v_max3_f32 v157, v157, v88, v72
	v_max3_f32 v156, v156, v89, v73
	v_max3_f32 v157, v157, v90, v74
	v_max3_f32 v156, v156, v91, v75
	v_max3_f32 v157, v157, v92, v76
	v_max3_f32 v156, v156, v93, v77
	v_max3_f32 v157, v157, v94, v78
	v_max3_f32 v156, v156, v95, v79
	v_max3_f32 v157, v156, v157, v157
	v_add_f32_e32 v156, 0x41000000, v143
	v_cmp_gt_f32_e32 vcc, v157, v156
	s_cbranch_vccnz .Latt_oB_nors_resc
.Latt_oB_nors:
	s_cmp_eq_u32 s90, 0
	s_cbranch_scc1 .Latt_oB_nors_gen
	v_exp_f32_e32 v80, v80
	v_exp_f32_e32 v81, v81
	v_exp_f32_e32 v82, v82
	v_exp_f32_e32 v83, v83
	v_exp_f32_e32 v84, v84
	v_exp_f32_e32 v85, v85
	v_exp_f32_e32 v86, v86
	v_exp_f32_e32 v87, v87
	s_waitcnt lgkmcnt(11)
	v_mfma_f32_32x32x16_bf16 v[48:63], v[32:35], v[112:115], 0
	v_cvt_pk_bf16_f32 v168, v80, v81
	v_cvt_pk_bf16_f32 v169, v82, v83
	v_cvt_pk_bf16_f32 v170, v84, v85
	v_cvt_pk_bf16_f32 v171, v86, v87
	v_mfma_f32_32x32x16_bf16 v[32:47], v[36:39], v[112:115], 0
	v_pk_add_f32 v[230:231], v[80:81], v[82:83]
	v_pk_add_f32 v[230:231], v[230:231], v[84:85]
	v_pk_add_f32 v[230:231], v[230:231], v[86:87]
	v_mfma_f32_32x32x16_bf16 v[48:63], v[152:155], v[96:99], v[48:63]
	v_mfma_f32_32x32x16_bf16 v[32:47], v[206:209], v[96:99], v[32:47]
	ds_read_b128 v[152:155], v165 offset:128
	ds_read_b128 v[206:209], v165 offset:160
	ds_read_b128 v[226:229], v165 offset:6784
	ds_read_b128 v[236:239], v165 offset:6816
	v_exp_f32_e32 v88, v88
	v_exp_f32_e32 v89, v89
	v_exp_f32_e32 v90, v90
	v_exp_f32_e32 v91, v91
	s_waitcnt lgkmcnt(11)
	v_mfma_f32_32x32x16_bf16 v[48:63], v[210:213], v[100:103], v[48:63]
	ds_read_b128 a[0:3], v240 offset:40544
	v_exp_f32_e32 v92, v92
	v_exp_f32_e32 v93, v93
	v_exp_f32_e32 v94, v94
	v_exp_f32_e32 v95, v95
	v_mfma_f32_32x32x16_bf16 v[32:47], v[218:221], v[100:103], v[32:47]
	v_mfma_f32_32x32x16_bf16 v[48:63], v[214:217], v[104:107], v[48:63]
	v_cvt_pk_bf16_f32 v80, v88, v89
	v_cvt_pk_bf16_f32 v81, v90, v91
	v_cvt_pk_bf16_f32 v82, v92, v93
	v_cvt_pk_bf16_f32 v83, v94, v95
	v_mfma_f32_32x32x16_bf16 v[32:47], v[222:225], v[104:107], v[32:47]
	s_waitcnt lgkmcnt(10)
	v_mfma_f32_32x32x16_bf16 v[0:15], v[176:179], v[168:171], v[0:15]
	v_pk_add_f32 v[230:231], v[230:231], v[88:89]
	v_pk_add_f32 v[230:231], v[230:231], v[90:91]
	v_pk_add_f32 v[230:231], v[230:231], v[92:93]
	v_pk_add_f32 v[230:231], v[230:231], v[94:95]
	v_mfma_f32_32x32x16_bf16 v[16:31], v[180:183], v[168:171], v[16:31]
	s_andn2_b64 vcc, exec, s[10:11]
	s_cbranch_vccnz .Latt_wskip_oB1
	s_waitcnt vmcnt(1)
	ds_write_b128 v162, v[120:123] offset:13312
	s_and_saveexec_b64 s[2:3], s[6:7]
	s_cbranch_execz .Latt_wk_oB1
	s_waitcnt vmcnt(0)
	ds_write_b128 v164, v[124:127] offset:13440

; template <int MODE>
; __device__ __forceinline__ void attn_pv(const LAS unsigned char* vb_, f32x16 (&st)[2], f32x16 (&ot)[2], float& mrun, float& lsum, const int ql, const int hf, const int lane) {
;     if (MODE != 1) {
;     float mx = max3f(st[0][0], st[1][0], st[0][1]), my = max3f(st[1][1], st[0][2], st[1][2]);
; #pragma unroll
;     for (int i = 3; i < 15; i += 2) { mx = max3f(mx, st[0][i], st[1][i]); my = max3f(my, st[0][i + 1], st[1][i + 1]); }
;     mx = max3f(mx, st[0][15], st[1][15]); mx = max3f(mx, my, my);
;     if (__builtin_amdgcn_ballot_w64(mx > mrun + 8.0f) != 0ull) {
;         mx = fmaxf(mx, shx32(mx, lane));
;         const float mnew = (mx > mrun + 8.0f) ? mx : mrun;
;         const float alpha = fexp2(mrun - mnew);
;         mrun = mnew; lsum *= alpha;
; #pragma unroll
;         for (int i = 0; i < 16; ++i) { ot[0][i] *= alpha; ot[1][i] *= alpha; }
;     }
;     float ps = 0.f;
; #pragma unroll
;     for (int kb = 0; kb < 2; ++kb)
; #pragma unroll
;         for (int i = 0; i < 16; ++i) { const float p = fexp2(st[kb][i] - mrun); st[kb][i] = p; ps += p; }
;     lsum += ps;
;     } else lsum += st[0][0];
; #pragma unroll
;     for (int kb = 0; kb < 2; ++kb)
; #pragma unroll
;         for (int sI = 0; sI < 2; ++sI) {
;             u32x4 pw = {pk_bf16(st[kb][8 * sI + 0], st[kb][8 * sI + 1]), pk_bf16(st[kb][8 * sI + 2], st[kb][8 * sI + 3]),
;                         pk_bf16(st[kb][8 * sI + 4], st[kb][8 * sI + 5]), pk_bf16(st[kb][8 * sI + 6], st[kb][8 * sI + 7])};
;             const bf16x8 pf = __builtin_bit_cast(bf16x8, pw);
; #pragma unroll
;             for (int db = 0; db < 2; ++db) {
;                 const LAS unsigned char* vp = vb_ + (db * 32 + ql) * VROW + (kb * 32 + 16 * sI + 4 * hf) * 2;
;                 const u32x2 v0 = *(const LAS u32x2*)vp, v1 = *(const LAS u32x2*)(vp + 16);
;                 u32x4 vw = {v0[0], v0[1], v1[0], v1[1]};
;                 ot[db] = att_mma<MODE>(__builtin_bit_cast(bf16x8, vw), pf, ot[db]);
;             }
;         }
; }
; template <int MODE>
; __device__ __forceinline__ void attn_phase(const Args& a, bool do_ctx, LAS unsigned char* lds, const int wid_s) {
;     ...
;             attn_pv<MODE>(ldsv + VBUF, sb, ot, mrun, lsum, ql, hf, lane);
;             if (t + 3 < nkt) ATT_WRITEK(kK, kR, 1);
;             if (t + 2 < nkt) ATT_WRITEV(vV, 0);
;             __syncthreads();
;         }
.Latt_wskip_oB1:
	s_waitcnt vmcnt(0)
	ds_write2_b64 v141, v[128:129], v[130:131] offset1:2
	v_exp_f32_e32 v64, v64
	v_exp_f32_e32 v65, v65
	v_exp_f32_e32 v66, v66
	v_exp_f32_e32 v67, v67
	s_waitcnt lgkmcnt(0)
	s_barrier
	v_mfma_f32_32x32x16_bf16 v[48:63], v[152:155], v[108:111], v[48:63]
	v_exp_f32_e32 v68, v68
	v_exp_f32_e32 v69, v69
	v_exp_f32_e32 v70, v70
	v_exp_f32_e32 v71, v71
	v_mfma_f32_32x32x16_bf16 v[0:15], v[184:187], v[80:83], v[0:15]
	v_mfma_f32_32x32x16_bf16 v[16:31], v[188:191], v[80:83], v[16:31]
	v_cvt_pk_bf16_f32 v168, v64, v65
	v_cvt_pk_bf16_f32 v169, v66, v67
	v_cvt_pk_bf16_f32 v170, v68, v69
	v_cvt_pk_bf16_f32 v171, v70, v71
	v_mfma_f32_32x32x16_bf16 v[32:47], v[226:229], v[108:111], v[32:47]
	v_pk_add_f32 v[230:231], v[230:231], v[64:65]
	v_pk_add_f32 v[230:231], v[230:231], v[66:67]
	v_pk_add_f32 v[230:231], v[230:231], v[68:69]
	v_pk_add_f32 v[230:231], v[230:231], v[70:71]
	v_mfma_f32_32x32x16_bf16 v[48:63], v[206:209], v[116:119], v[48:63]
	v_mfma_f32_32x32x16_bf16 v[32:47], v[236:239], v[116:119], v[32:47]
	v_exp_f32_e32 v72, v72
	v_exp_f32_e32 v73, v73
	v_exp_f32_e32 v74, v74
	v_exp_f32_e32 v75, v75
	v_mfma_f32_32x32x16_bf16 v[0:15], v[192:195], v[168:171], v[0:15]
	v_exp_f32_e32 v76, v76
	v_exp_f32_e32 v77, v77
	v_exp_f32_e32 v78, v78
	v_exp_f32_e32 v79, v79
	v_mfma_f32_32x32x16_bf16 v[16:31], v[196:199], v[168:171], v[16:31]
	v_cvt_pk_bf16_f32 v80, v72, v73
	v_cvt_pk_bf16_f32 v81, v74, v75
	v_cvt_pk_bf16_f32 v82, v76, v77
	v_cvt_pk_bf16_f32 v83, v78, v79
	v_pk_add_f32 v[230:231], v[230:231], v[72:73]
	v_pk_add_f32 v[230:231], v[230:231], v[74:75]
	v_pk_add_f32 v[230:231], v[230:231], v[76:77]
	v_pk_add_f32 v[230:231], v[230:231], v[78:79]
	v_add_f32_e32 v230, v230, v231
	v_add_f32_e32 v167, v167, v230
	v_mfma_f32_32x32x16_bf16 v[0:15], v[172:175], v[80:83], v[0:15]
	v_mfma_f32_32x32x16_bf16 v[16:31], a[0:3], v[80:83], v[16:31]
.Latt_oB_nors_join:
	s_add_u32 s80, s80, 0x20000
	s_addc_u32 s81, s81, 0
	s_add_u32 s82, s82, 0x2000
	s_addc_u32 s83, s83, 0
	s_add_u32 s84, s84, 0x100
	s_addc_u32 s85, s85, 0
	s_add_i32 s12, s12, 2
	s_branch .LBB0_435

; #define LAS __attribute__((address_space(3)))
; __device__ __forceinline__ unsigned pk_bf16(float lo, float hi) { unsigned r; asm("v_cvt_pk_bf16_f32 %0, %1, %2" : "=v"(r) : "v"(lo), "v"(hi)); return r; }
; __device__ __forceinline__ float fexp2(float x) { return __builtin_amdgcn_exp2f(x); }
; template <int MODE>
; __device__ __forceinline__ void attn_pv(const LAS unsigned char* vb_, f32x16 (&st)[2], f32x16 (&ot)[2], float& mrun, float& lsum, const int ql, const int hf, const int lane) {
;     ...
;     float ps = 0.f;
; #pragma unroll
;     for (int kb = 0; kb < 2; ++kb)
; #pragma unroll
;         for (int i = 0; i < 16; ++i) { const float p = fexp2(st[kb][i] - mrun); st[kb][i] = p; ps += p; }
;     lsum += ps;
;     } else lsum += st[0][0];
; #pragma unroll
;     for (int kb = 0; kb < 2; ++kb)
; #pragma unroll
;         for (int sI = 0; sI < 2; ++sI) {
;             u32x4 pw = {pk_bf16(st[kb][8 * sI + 0], st[kb][8 * sI + 1]), pk_bf16(st[kb][8 * sI + 2], st[kb][8 * sI + 3]),
;                         pk_bf16(st[kb][8 * sI + 4], st[kb][8 * sI + 5]), pk_bf16(st[kb][8 * sI + 6], st[kb][8 * sI + 7])};
;             const bf16x8 pf = __builtin_bit_cast(bf16x8, pw);
; #pragma unroll
;             for (int db = 0; db < 2; ++db) {
;                 const LAS unsigned char* vp = vb_ + (db * 32 + ql) * VROW + (kb * 32 + 16 * sI + 4 * hf) * 2;
;                 const u32x2 v0 = *(const LAS u32x2*)vp, v1 = *(const LAS u32x2*)(vp + 16);
;                 u32x4 vw = {v0[0], v0[1], v1[0], v1[1]};
;                 ot[db] = att_mma<MODE>(__builtin_bit_cast(bf16x8, vw), pf, ot[db]);
;             }
;         }
; }
.Latt_ot_nors_gen:
	v_sub_f32_e32 v80, v80, v143
	v_sub_f32_e32 v81, v81, v143
	v_sub_f32_e32 v82, v82, v143
	v_sub_f32_e32 v83, v83, v143
	v_sub_f32_e32 v84, v84, v143
	v_sub_f32_e32 v85, v85, v143
	v_sub_f32_e32 v86, v86, v143
	v_sub_f32_e32 v87, v87, v143
	v_exp_f32_e32 v80, v80
	v_exp_f32_e32 v81, v81
	v_exp_f32_e32 v82, v82
	v_exp_f32_e32 v83, v83
	v_exp_f32_e32 v84, v84
	v_exp_f32_e32 v85, v85
	v_exp_f32_e32 v86, v86
	v_exp_f32_e32 v87, v87
	v_cvt_pk_bf16_f32 v168, v80, v81
	v_cvt_pk_bf16_f32 v169, v82, v83
	v_cvt_pk_bf16_f32 v170, v84, v85
	v_cvt_pk_bf16_f32 v171, v86, v87
	v_pk_add_f32 v[230:231], v[80:81], v[82:83]
	v_pk_add_f32 v[230:231], v[230:231], v[84:85]
	v_pk_add_f32 v[230:231], v[230:231], v[86:87]
	v_sub_f32_e32 v88, v88, v143
	v_sub_f32_e32 v89, v89, v143
	v_sub_f32_e32 v90, v90, v143
	v_sub_f32_e32 v91, v91, v143
	v_sub_f32_e32 v92, v92, v143
	v_sub_f32_e32 v93, v93, v143
	v_sub_f32_e32 v94, v94, v143
	v_sub_f32_e32 v95, v95, v143
	v_exp_f32_e32 v88, v88
	v_exp_f32_e32 v89, v89
	v_exp_f32_e32 v90, v90
	v_exp_f32_e32 v91, v91
	s_waitcnt lgkmcnt(0)
	v_mfma_f32_32x32x16_bf16 v[0:15], v[176:179], v[168:171], v[0:15]
	v_exp_f32_e32 v92, v92
	v_exp_f32_e32 v93, v93
	v_exp_f32_e32 v94, v94
	v_exp_f32_e32 v95, v95
	v_mfma_f32_32x32x16_bf16 v[16:31], v[180:183], v[168:171], v[16:31]
	v_cvt_pk_bf16_f32 v80, v88, v89
	v_cvt_pk_bf16_f32 v81, v90, v91
	v_cvt_pk_bf16_f32 v82, v92, v93
	v_cvt_pk_bf16_f32 v83, v94, v95
	v_pk_add_f32 v[230:231], v[230:231], v[88:89]
	v_pk_add_f32 v[230:231], v[230:231], v[90:91]
	v_pk_add_f32 v[230:231], v[230:231], v[92:93]
	v_pk_add_f32 v[230:231], v[230:231], v[94:95]
	v_sub_f32_e32 v64, v64, v143
	v_sub_f32_e32 v65, v65, v143
	v_sub_f32_e32 v66, v66, v143
	v_sub_f32_e32 v67, v67, v143
	v_sub_f32_e32 v68, v68, v143
	v_sub_f32_e32 v69, v69, v143
	v_sub_f32_e32 v70, v70, v143
	v_sub_f32_e32 v71, v71, v143
	v_mfma_f32_32x32x16_bf16 v[0:15], v[184:187], v[80:83], v[0:15]
	v_exp_f32_e32 v64, v64
	v_exp_f32_e32 v65, v65
	v_exp_f32_e32 v66, v66
	v_exp_f32_e32 v67, v67
	v_mfma_f32_32x32x16_bf16 v[16:31], v[188:191], v[80:83], v[16:31]
	v_exp_f32_e32 v68, v68
	v_exp_f32_e32 v69, v69
	v_exp_f32_e32 v70, v70
	v_exp_f32_e32 v71, v71
	v_cvt_pk_bf16_f32 v168, v64, v65
	v_cvt_pk_bf16_f32 v169, v66, v67
	v_cvt_pk_bf16_f32 v170, v68, v69
	v_cvt_pk_bf16_f32 v171, v70, v71
	v_pk_add_f32 v[230:231], v[230:231], v[64:65]
	v_pk_add_f32 v[230:231], v[230:231], v[66:67]
	v_pk_add_f32 v[230:231], v[230:231], v[68:69]
	v_pk_add_f32 v[230:231], v[230:231], v[70:71]
	v_sub_f32_e32 v72, v72, v143
	v_sub_f32_e32 v73, v73, v143
	v_sub_f32_e32 v74, v74, v143
	v_sub_f32_e32 v75, v75, v143
	v_sub_f32_e32 v76, v76, v143
	v_sub_f32_e32 v77, v77, v143
	v_sub_f32_e32 v78, v78, v143
	v_sub_f32_e32 v79, v79, v143
	v_mfma_f32_32x32x16_bf16 v[0:15], v[192:195], v[168:171], v[0:15]
	v_exp_f32_e32 v72, v72
	v_exp_f32_e32 v73, v73
	v_exp_f32_e32 v74, v74
	v_exp_f32_e32 v75, v75
	v_mfma_f32_32x32x16_bf16 v[16:31], v[196:199], v[168:171], v[16:31]
	v_exp_f32_e32 v76, v76
	v_exp_f32_e32 v77, v77
	v_exp_f32_e32 v78, v78
	v_exp_f32_e32 v79, v79
	v_cvt_pk_bf16_f32 v80, v72, v73
	v_cvt_pk_bf16_f32 v81, v74, v75
	v_cvt_pk_bf16_f32 v82, v76, v77
	v_cvt_pk_bf16_f32 v83, v78, v79
	v_pk_add_f32 v[230:231], v[230:231], v[72:73]
	v_pk_add_f32 v[230:231], v[230:231], v[74:75]
	v_pk_add_f32 v[230:231], v[230:231], v[76:77]
	v_pk_add_f32 v[230:231], v[230:231], v[78:79]
	v_add_f32_e32 v230, v230, v231
	v_add_f32_e32 v167, v167, v230
	v_mfma_f32_32x32x16_bf16 v[0:15], v[172:175], v[80:83], v[0:15]
	v_mfma_f32_32x32x16_bf16 v[16:31], a[0:3], v[80:83], v[16:31]
	s_branch .Latt_ot_nors_join
; #define LAS __attribute__((address_space(3)))
; __device__ __forceinline__ float shx32(float v, int lane) { return __int_as_float(__builtin_amdgcn_ds_bpermute((lane ^ 32) << 2, __float_as_int(v))); }
; __device__ __forceinline__ unsigned pk_bf16(float lo, float hi) { unsigned r; asm("v_cvt_pk_bf16_f32 %0, %1, %2" : "=v"(r) : "v"(lo), "v"(hi)); return r; }
; __device__ __forceinline__ float fexp2(float x) { return __builtin_amdgcn_exp2f(x); }
; template <int MODE>
; __device__ __forceinline__ void attn_pv(const LAS unsigned char* vb_, f32x16 (&st)[2], f32x16 (&ot)[2], float& mrun, float& lsum, const int ql, const int hf, const int lane) {
;     ...
;     if (__builtin_amdgcn_ballot_w64(mx > mrun + 8.0f) != 0ull) {
;         mx = fmaxf(mx, shx32(mx, lane));
;         const float mnew = (mx > mrun + 8.0f) ? mx : mrun;
;         const float alpha = fexp2(mrun - mnew);
;         mrun = mnew; lsum *= alpha;
; #pragma unroll
;         for (int i = 0; i < 16; ++i) { ot[0][i] *= alpha; ot[1][i] *= alpha; }
;     }
;     float ps = 0.f;
; #pragma unroll
;     for (int kb = 0; kb < 2; ++kb)
; #pragma unroll
;         for (int i = 0; i < 16; ++i) { const float p = fexp2(st[kb][i] - mrun); st[kb][i] = p; ps += p; }
;     lsum += ps;
;     } else lsum += st[0][0];
; #pragma unroll
;     for (int kb = 0; kb < 2; ++kb)
; #pragma unroll
;         for (int sI = 0; sI < 2; ++sI) {
;             u32x4 pw = {pk_bf16(st[kb][8 * sI + 0], st[kb][8 * sI + 1]), pk_bf16(st[kb][8 * sI + 2], st[kb][8 * sI + 3]),
;                         pk_bf16(st[kb][8 * sI + 4], st[kb][8 * sI + 5]), pk_bf16(st[kb][8 * sI + 6], st[kb][8 * sI + 7])};
;             const bf16x8 pf = __builtin_bit_cast(bf16x8, pw);
; #pragma unroll
;             for (int db = 0; db < 2; ++db) {
;                 const LAS unsigned char* vp = vb_ + (db * 32 + ql) * VROW + (kb * 32 + 16 * sI + 4 * hf) * 2;
;                 const u32x2 v0 = *(const LAS u32x2*)vp, v1 = *(const LAS u32x2*)(vp + 16);
;                 u32x4 vw = {v0[0], v0[1], v1[0], v1[1]};
;                 ot[db] = att_mma<MODE>(__builtin_bit_cast(bf16x8, vw), pf, ot[db]);
;             }
;         }
; }
.Latt_eB_nors_resc:
	ds_bpermute_b32 v231, v163, v157
	v_max_f32_e32 v157, v157, v157
	s_waitcnt lgkmcnt(0)
	v_max_f32_e32 v231, v231, v231
	v_max_f32_e32 v157, v157, v231
	v_cmp_gt_f32_e32 vcc, v157, v156
	s_nop 1
	v_cndmask_b32_e32 v157, v143, v157, vcc
	v_add_f32_e32 v231, 0x41400000, v157
	s_mov_b32 s2, 0x41a00000
	v_cmp_le_f32_e64 vcc, |v231|, s2
	s_nop 1
	v_cndmask_b32_e32 v157, v157, v201, vcc
	v_sub_f32_e32 v143, v143, v157
	v_exp_f32_e32 v156, v143
	v_mov_b32_e32 v143, v157
	v_mul_f32_e32 v167, v167, v156
	v_pk_mul_f32 v[14:15], v[14:15], v[156:157] op_sel_hi:[1,0]
	v_pk_mul_f32 v[12:13], v[12:13], v[156:157] op_sel_hi:[1,0]
	v_pk_mul_f32 v[10:11], v[10:11], v[156:157] op_sel_hi:[1,0]
	v_pk_mul_f32 v[8:9], v[8:9], v[156:157] op_sel_hi:[1,0]
	v_pk_mul_f32 v[6:7], v[6:7], v[156:157] op_sel_hi:[1,0]
	v_pk_mul_f32 v[4:5], v[4:5], v[156:157] op_sel_hi:[1,0]
	v_pk_mul_f32 v[2:3], v[2:3], v[156:157] op_sel_hi:[1,0]
	v_pk_mul_f32 v[0:1], v[0:1], v[156:157] op_sel_hi:[1,0]
	v_pk_mul_f32 v[30:31], v[30:31], v[156:157] op_sel_hi:[1,0]
	v_pk_mul_f32 v[28:29], v[28:29], v[156:157] op_sel_hi:[1,0]
	v_pk_mul_f32 v[26:27], v[26:27], v[156:157] op_sel_hi:[1,0]
	v_pk_mul_f32 v[24:25], v[24:25], v[156:157] op_sel_hi:[1,0]
	v_pk_mul_f32 v[22:23], v[22:23], v[156:157] op_sel_hi:[1,0]
	v_pk_mul_f32 v[20:21], v[20:21], v[156:157] op_sel_hi:[1,0]
	v_pk_mul_f32 v[18:19], v[18:19], v[156:157] op_sel_hi:[1,0]
	v_pk_mul_f32 v[16:17], v[16:17], v[156:157] op_sel_hi:[1,0]
	v_cmp_neq_f32_e32 vcc, 0, v143
	s_nop 1
	s_cmp_eq_u64 vcc, 0
	s_cselect_b32 s90, 1, 0
	s_branch .Latt_eB_nors
.Latt_eB_nors_gen:
	v_sub_f32_e32 v48, v48, v143
	v_sub_f32_e32 v49, v49, v143
	v_sub_f32_e32 v50, v50, v143
	v_sub_f32_e32 v51, v51, v143
	v_sub_f32_e32 v52, v52, v143
	v_sub_f32_e32 v53, v53, v143
	v_sub_f32_e32 v54, v54, v143
	v_sub_f32_e32 v55, v55, v143
	v_exp_f32_e32 v48, v48
	v_exp_f32_e32 v49, v49
	v_exp_f32_e32 v50, v50
	v_exp_f32_e32 v51, v51
	v_exp_f32_e32 v52, v52
	v_exp_f32_e32 v53, v53
	v_exp_f32_e32 v54, v54
	v_exp_f32_e32 v55, v55
	s_waitcnt lgkmcnt(11)
	v_mfma_f32_32x32x16_bf16 v[80:95], v[64:67], v[112:115], 0
	v_cvt_pk_bf16_f32 v152, v48, v49
	v_cvt_pk_bf16_f32 v153, v50, v51
	v_cvt_pk_bf16_f32 v154, v52, v53
	v_cvt_pk_bf16_f32 v155, v54, v55
	v_mfma_f32_32x32x16_bf16 v[64:79], v[68:71], v[112:115], 0
	v_pk_add_f32 v[230:231], v[48:49], v[50:51]
	v_pk_add_f32 v[230:231], v[230:231], v[52:53]
	v_pk_add_f32 v[230:231], v[230:231], v[54:55]
	v_mfma_f32_32x32x16_bf16 v[80:95], v[168:171], v[96:99], v[80:95]
	v_sub_f32_e32 v56, v56, v143
	v_sub_f32_e32 v57, v57, v143
	v_sub_f32_e32 v58, v58, v143
	v_sub_f32_e32 v59, v59, v143
	v_sub_f32_e32 v60, v60, v143
	v_sub_f32_e32 v61, v61, v143
	v_sub_f32_e32 v62, v62, v143
	v_sub_f32_e32 v63, v63, v143
	v_mfma_f32_32x32x16_bf16 v[64:79], v[172:175], v[96:99], v[64:79]
	ds_read_b128 v[168:171], v165 offset:13440
	ds_read_b128 v[172:175], v165 offset:13472
	ds_read_b128 v[192:195], v165 offset:20096
	ds_read_b128 v[196:199], v165 offset:20128
	v_exp_f32_e32 v56, v56
	v_exp_f32_e32 v57, v57
	v_exp_f32_e32 v58, v58
	v_exp_f32_e32 v59, v59
	s_waitcnt lgkmcnt(11)
	v_mfma_f32_32x32x16_bf16 v[80:95], v[176:179], v[100:103], v[80:95]
	ds_read_b128 a[0:3], v240 offset:31328
	v_exp_f32_e32 v60, v60
	v_exp_f32_e32 v61, v61
	v_exp_f32_e32 v62, v62
	v_exp_f32_e32 v63, v63
	v_mfma_f32_32x32x16_bf16 v[64:79], v[184:187], v[100:103], v[64:79]
	v_mfma_f32_32x32x16_bf16 v[80:95], v[180:183], v[104:107], v[80:95]
	v_cvt_pk_bf16_f32 v48, v56, v57
	v_cvt_pk_bf16_f32 v49, v58, v59
	v_cvt_pk_bf16_f32 v50, v60, v61
	v_cvt_pk_bf16_f32 v51, v62, v63
	v_mfma_f32_32x32x16_bf16 v[64:79], v[188:191], v[104:107], v[64:79]
	s_waitcnt lgkmcnt(10)
	v_mfma_f32_32x32x16_bf16 v[16:31], v[206:209], v[152:155], v[16:31]
	v_pk_add_f32 v[230:231], v[230:231], v[56:57]
	v_pk_add_f32 v[230:231], v[230:231], v[58:59]
	v_pk_add_f32 v[230:231], v[230:231], v[60:61]
	v_pk_add_f32 v[230:231], v[230:231], v[62:63]
	v_mfma_f32_32x32x16_bf16 v[0:15], v[210:213], v[152:155], v[0:15]
	s_andn2_b64 vcc, exec, s[10:11]
	s_cbranch_vccnz .Latt_wskip_eB2
	s_waitcnt vmcnt(2)
	ds_write_b128 v162, v[120:123]
	s_and_saveexec_b64 s[2:3], s[6:7]
	s_cbranch_execz .Latt_wk_eB2
	s_waitcnt vmcnt(1)
	ds_write_b128 v164, v[124:127] offset:128

; #define LAS __attribute__((address_space(3)))
; __device__ __forceinline__ unsigned pk_bf16(float lo, float hi) { unsigned r; asm("v_cvt_pk_bf16_f32 %0, %1, %2" : "=v"(r) : "v"(lo), "v"(hi)); return r; }
; __device__ __forceinline__ float fexp2(float x) { return __builtin_amdgcn_exp2f(x); }
; #define ATT_WRITEV(rv, buf) do { LAS u32x2* p_ = (LAS u32x2*)(ldsv + (buf) * VBUF + svt); u32x2 lo_ = {rv[0], rv[1]}, hi_ = {rv[2], rv[3]}; p_[0] = lo_; p_[1] = hi_; } while (0)
; template <int MODE>
; __device__ __forceinline__ void attn_pv(const LAS unsigned char* vb_, f32x16 (&st)[2], f32x16 (&ot)[2], float& mrun, float& lsum, const int ql, const int hf, const int lane) {
;     ...
;     float ps = 0.f;
; #pragma unroll
;     for (int kb = 0; kb < 2; ++kb)
; #pragma unroll
;         for (int i = 0; i < 16; ++i) { const float p = fexp2(st[kb][i] - mrun); st[kb][i] = p; ps += p; }
;     lsum += ps;
;     } else lsum += st[0][0];
; #pragma unroll
;     for (int kb = 0; kb < 2; ++kb)
; #pragma unroll
;         for (int sI = 0; sI < 2; ++sI) {
;             u32x4 pw = {pk_bf16(st[kb][8 * sI + 0], st[kb][8 * sI + 1]), pk_bf16(st[kb][8 * sI + 2], st[kb][8 * sI + 3]),
;                         pk_bf16(st[kb][8 * sI + 4], st[kb][8 * sI + 5]), pk_bf16(st[kb][8 * sI + 6], st[kb][8 * sI + 7])};
;             const bf16x8 pf = __builtin_bit_cast(bf16x8, pw);
; #pragma unroll
;             for (int db = 0; db < 2; ++db) {
;                 const LAS unsigned char* vp = vb_ + (db * 32 + ql) * VROW + (kb * 32 + 16 * sI + 4 * hf) * 2;
;                 const u32x2 v0 = *(const LAS u32x2*)vp, v1 = *(const LAS u32x2*)(vp + 16);
;                 u32x4 vw = {v0[0], v0[1], v1[0], v1[1]};
;                 ot[db] = att_mma<MODE>(__builtin_bit_cast(bf16x8, vw), pf, ot[db]);
;             }
;         }
; }
; template <int MODE>
; __device__ __forceinline__ void attn_phase(const Args& a, bool do_ctx, LAS unsigned char* lds, const int wid_s) {
;     ...
;             ATT_WRITEV(vV, 1);
;             __syncthreads();
.Latt_wskip_eB2:
	s_waitcnt vmcnt(0)
	ds_write2_b64 v251, v[128:129], v[130:131] offset1:2
	v_sub_f32_e32 v32, v32, v143
	v_sub_f32_e32 v33, v33, v143
	v_sub_f32_e32 v34, v34, v143
	v_sub_f32_e32 v35, v35, v143
	v_sub_f32_e32 v36, v36, v143
	v_sub_f32_e32 v37, v37, v143
	v_sub_f32_e32 v38, v38, v143
	v_sub_f32_e32 v39, v39, v143
	v_exp_f32_e32 v32, v32
	v_exp_f32_e32 v33, v33
	v_exp_f32_e32 v34, v34
	v_exp_f32_e32 v35, v35
	s_waitcnt lgkmcnt(0)
	s_barrier
	v_mfma_f32_32x32x16_bf16 v[80:95], v[168:171], v[108:111], v[80:95]
	v_exp_f32_e32 v36, v36
	v_exp_f32_e32 v37, v37
	v_exp_f32_e32 v38, v38
	v_exp_f32_e32 v39, v39
	v_mfma_f32_32x32x16_bf16 v[16:31], v[214:217], v[48:51], v[16:31]
	v_mfma_f32_32x32x16_bf16 v[0:15], v[218:221], v[48:51], v[0:15]
	v_cvt_pk_bf16_f32 v152, v32, v33
	v_cvt_pk_bf16_f32 v153, v34, v35
	v_cvt_pk_bf16_f32 v154, v36, v37
	v_cvt_pk_bf16_f32 v155, v38, v39
	v_mfma_f32_32x32x16_bf16 v[64:79], v[192:195], v[108:111], v[64:79]
	v_pk_add_f32 v[230:231], v[230:231], v[32:33]
	v_pk_add_f32 v[230:231], v[230:231], v[34:35]
	v_pk_add_f32 v[230:231], v[230:231], v[36:37]
	v_pk_add_f32 v[230:231], v[230:231], v[38:39]
	v_mfma_f32_32x32x16_bf16 v[80:95], v[172:175], v[116:119], v[80:95]
	v_sub_f32_e32 v40, v40, v143
	v_sub_f32_e32 v41, v41, v143
	v_sub_f32_e32 v42, v42, v143
	v_sub_f32_e32 v43, v43, v143
	v_sub_f32_e32 v44, v44, v143
	v_sub_f32_e32 v45, v45, v143
	v_sub_f32_e32 v46, v46, v143
	v_sub_f32_e32 v47, v47, v143
	v_mfma_f32_32x32x16_bf16 v[64:79], v[196:199], v[116:119], v[64:79]
	v_exp_f32_e32 v40, v40
	v_exp_f32_e32 v41, v41
	v_exp_f32_e32 v42, v42
	v_exp_f32_e32 v43, v43
	v_mfma_f32_32x32x16_bf16 v[16:31], v[222:225], v[152:155], v[16:31]
	v_exp_f32_e32 v44, v44
	v_exp_f32_e32 v45, v45
	v_exp_f32_e32 v46, v46
	v_exp_f32_e32 v47, v47
	v_mfma_f32_32x32x16_bf16 v[0:15], v[226:229], v[152:155], v[0:15]
	v_cvt_pk_bf16_f32 v48, v40, v41
	v_cvt_pk_bf16_f32 v49, v42, v43
	v_cvt_pk_bf16_f32 v50, v44, v45
	v_cvt_pk_bf16_f32 v51, v46, v47
	v_pk_add_f32 v[230:231], v[230:231], v[40:41]
	v_pk_add_f32 v[230:231], v[230:231], v[42:43]
	v_pk_add_f32 v[230:231], v[230:231], v[44:45]
	v_pk_add_f32 v[230:231], v[230:231], v[46:47]
	v_add_f32_e32 v230, v230, v231
	v_add_f32_e32 v167, v167, v230
	v_mfma_f32_32x32x16_bf16 v[0:15], v[236:239], v[48:51], v[0:15]
	v_mfma_f32_32x32x16_bf16 v[16:31], a[0:3], v[48:51], v[16:31]
	s_branch .Latt_eB_nors_join

; #define LAS __attribute__((address_space(3)))
; __device__ __forceinline__ float shx32(float v, int lane) { return __int_as_float(__builtin_amdgcn_ds_bpermute((lane ^ 32) << 2, __float_as_int(v))); }
; __device__ __forceinline__ unsigned pk_bf16(float lo, float hi) { unsigned r; asm("v_cvt_pk_bf16_f32 %0, %1, %2" : "=v"(r) : "v"(lo), "v"(hi)); return r; }
; template <int MODE>
; __device__ __forceinline__ void attn_pv(const LAS unsigned char* vb_, f32x16 (&st)[2], f32x16 (&ot)[2], float& mrun, float& lsum, const int ql, const int hf, const int lane) {
;     if (MODE != 1) {
;     float mx = max3f(st[0][0], st[1][0], st[0][1]), my = max3f(st[1][1], st[0][2], st[1][2]);
; #pragma unroll
;     for (int i = 3; i < 15; i += 2) { mx = max3f(mx, st[0][i], st[1][i]); my = max3f(my, st[0][i + 1], st[1][i + 1]); }
;     mx = max3f(mx, st[0][15], st[1][15]); mx = max3f(mx, my, my);
;     if (__builtin_amdgcn_ballot_w64(mx > mrun + 8.0f) != 0ull) {
;         mx = fmaxf(mx, shx32(mx, lane));
;         const float mnew = (mx > mrun + 8.0f) ? mx : mrun;
;         const float alpha = fexp2(mrun - mnew);
;         mrun = mnew; lsum *= alpha;
; #pragma unroll
;         for (int i = 0; i < 16; ++i) { ot[0][i] *= alpha; ot[1][i] *= alpha; }
;     }
;     float ps = 0.f;
; #pragma unroll
;     for (int kb = 0; kb < 2; ++kb)
; #pragma unroll
;         for (int i = 0; i < 16; ++i) { const float p = fexp2(st[kb][i] - mrun); st[kb][i] = p; ps += p; }
;     lsum += ps;
;     } else lsum += st[0][0];
; #pragma unroll
;     for (int kb = 0; kb < 2; ++kb)
; #pragma unroll
;         for (int sI = 0; sI < 2; ++sI) {
;             u32x4 pw = {pk_bf16(st[kb][8 * sI + 0], st[kb][8 * sI + 1]), pk_bf16(st[kb][8 * sI + 2], st[kb][8 * sI + 3]),
;                         pk_bf16(st[kb][8 * sI + 4], st[kb][8 * sI + 5]), pk_bf16(st[kb][8 * sI + 6], st[kb][8 * sI + 7])};
;             const bf16x8 pf = __builtin_bit_cast(bf16x8, pw);
; #pragma unroll
;             for (int db = 0; db < 2; ++db) {
;                 const LAS unsigned char* vp = vb_ + (db * 32 + ql) * VROW + (kb * 32 + 16 * sI + 4 * hf) * 2;
;                 const u32x2 v0 = *(const LAS u32x2*)vp, v1 = *(const LAS u32x2*)(vp + 16);
;                 u32x4 vw = {v0[0], v0[1], v1[0], v1[1]};
;                 ot[db] = att_mma<MODE>(__builtin_bit_cast(bf16x8, vw), pf, ot[db]);
;             }
;         }
; }
.Latt_oB_nors_gen:
	v_sub_f32_e32 v80, v80, v143
	v_sub_f32_e32 v81, v81, v143
	v_sub_f32_e32 v82, v82, v143
	v_sub_f32_e32 v83, v83, v143
	v_sub_f32_e32 v84, v84, v143
	v_sub_f32_e32 v85, v85, v143
	v_sub_f32_e32 v86, v86, v143
	v_sub_f32_e32 v87, v87, v143
	v_exp_f32_e32 v80, v80
	v_exp_f32_e32 v81, v81
	v_exp_f32_e32 v82, v82
	v_exp_f32_e32 v83, v83
	v_exp_f32_e32 v84, v84
	v_exp_f32_e32 v85, v85
	v_exp_f32_e32 v86, v86
	v_exp_f32_e32 v87, v87
	s_waitcnt lgkmcnt(11)
	v_mfma_f32_32x32x16_bf16 v[48:63], v[32:35], v[112:115], 0
	v_cvt_pk_bf16_f32 v168, v80, v81
	v_cvt_pk_bf16_f32 v169, v82, v83
	v_cvt_pk_bf16_f32 v170, v84, v85
	v_cvt_pk_bf16_f32 v171, v86, v87
	v_mfma_f32_32x32x16_bf16 v[32:47], v[36:39], v[112:115], 0
	v_pk_add_f32 v[230:231], v[80:81], v[82:83]
	v_pk_add_f32 v[230:231], v[230:231], v[84:85]
	v_pk_add_f32 v[230:231], v[230:231], v[86:87]
	v_mfma_f32_32x32x16_bf16 v[48:63], v[152:155], v[96:99], v[48:63]
	v_sub_f32_e32 v88, v88, v143
	v_sub_f32_e32 v89, v89, v143
	v_sub_f32_e32 v90, v90, v143
	v_sub_f32_e32 v91, v91, v143
	v_sub_f32_e32 v92, v92, v143
	v_sub_f32_e32 v93, v93, v143
	v_sub_f32_e32 v94, v94, v143
	v_sub_f32_e32 v95, v95, v143
	v_mfma_f32_32x32x16_bf16 v[32:47], v[206:209], v[96:99], v[32:47]
	ds_read_b128 v[152:155], v165 offset:128
	ds_read_b128 v[206:209], v165 offset:160
	ds_read_b128 v[226:229], v165 offset:6784
	ds_read_b128 v[236:239], v165 offset:6816
	v_exp_f32_e32 v88, v88
	v_exp_f32_e32 v89, v89
	v_exp_f32_e32 v90, v90
	v_exp_f32_e32 v91, v91
	s_waitcnt lgkmcnt(11)
	v_mfma_f32_32x32x16_bf16 v[48:63], v[210:213], v[100:103], v[48:63]
	ds_read_b128 a[0:3], v240 offset:40544
	v_exp_f32_e32 v92, v92
	v_exp_f32_e32 v93, v93
	v_exp_f32_e32 v94, v94
	v_exp_f32_e32 v95, v95
	v_mfma_f32_32x32x16_bf16 v[32:47], v[218:221], v[100:103], v[32:47]
	v_mfma_f32_32x32x16_bf16 v[48:63], v[214:217], v[104:107], v[48:63]
	v_cvt_pk_bf16_f32 v80, v88, v89
	v_cvt_pk_bf16_f32 v81, v90, v91
	v_cvt_pk_bf16_f32 v82, v92, v93
	v_cvt_pk_bf16_f32 v83, v94, v95
	v_mfma_f32_32x32x16_bf16 v[32:47], v[222:225], v[104:107], v[32:47]
	s_waitcnt lgkmcnt(10)
	v_mfma_f32_32x32x16_bf16 v[0:15], v[176:179], v[168:171], v[0:15]
	v_pk_add_f32 v[230:231], v[230:231], v[88:89]
	v_pk_add_f32 v[230:231], v[230:231], v[90:91]
	v_pk_add_f32 v[230:231], v[230:231], v[92:93]
	v_pk_add_f32 v[230:231], v[230:231], v[94:95]
	v_mfma_f32_32x32x16_bf16 v[16:31], v[180:183], v[168:171], v[16:31]
	s_andn2_b64 vcc, exec, s[10:11]
	s_cbranch_vccnz .Latt_wskip_oB2
	s_waitcnt vmcnt(1)
	ds_write_b128 v162, v[120:123] offset:13312
	s_and_saveexec_b64 s[2:3], s[6:7]
	s_cbranch_execz .Latt_wk_oB2
	s_waitcnt vmcnt(0)
	ds_write_b128 v164, v[124:127] offset:13440

; #define LAS __attribute__((address_space(3)))
; __device__ __forceinline__ unsigned pk_bf16(float lo, float hi) { unsigned r; asm("v_cvt_pk_bf16_f32 %0, %1, %2" : "=v"(r) : "v"(lo), "v"(hi)); return r; }
; __device__ __forceinline__ float fexp2(float x) { return __builtin_amdgcn_exp2f(x); }
; #define ATT_WRITEK(rk, rr, buf) do { LAS unsigned char* nb_ = lds + (buf) * KBUF; *(LAS u32x4*)(nb_ + skn) = rk; if (tid < 256) *(LAS u32x4*)(nb_ + skr) = rr; } while (0)
; #define ATT_WRITEV(rv, buf) do { LAS u32x2* p_ = (LAS u32x2*)(ldsv + (buf) * VBUF + svt); u32x2 lo_ = {rv[0], rv[1]}, hi_ = {rv[2], rv[3]}; p_[0] = lo_; p_[1] = hi_; } while (0)
; template <int MODE>
; __device__ __forceinline__ void attn_pv(const LAS unsigned char* vb_, f32x16 (&st)[2], f32x16 (&ot)[2], float& mrun, float& lsum, const int ql, const int hf, const int lane) {
;     ...
;     float ps = 0.f;
; #pragma unroll
;     for (int kb = 0; kb < 2; ++kb)
; #pragma unroll
;         for (int i = 0; i < 16; ++i) { const float p = fexp2(st[kb][i] - mrun); st[kb][i] = p; ps += p; }
;     lsum += ps;
;     } else lsum += st[0][0];
; #pragma unroll
;     for (int kb = 0; kb < 2; ++kb)
; #pragma unroll
;         for (int sI = 0; sI < 2; ++sI) {
;             u32x4 pw = {pk_bf16(st[kb][8 * sI + 0], st[kb][8 * sI + 1]), pk_bf16(st[kb][8 * sI + 2], st[kb][8 * sI + 3]),
;                         pk_bf16(st[kb][8 * sI + 4], st[kb][8 * sI + 5]), pk_bf16(st[kb][8 * sI + 6], st[kb][8 * sI + 7])};
;             const bf16x8 pf = __builtin_bit_cast(bf16x8, pw);
; #pragma unroll
;             for (int db = 0; db < 2; ++db) {
;                 const LAS unsigned char* vp = vb_ + (db * 32 + ql) * VROW + (kb * 32 + 16 * sI + 4 * hf) * 2;
;                 const u32x2 v0 = *(const LAS u32x2*)vp, v1 = *(const LAS u32x2*)(vp + 16);
;                 u32x4 vw = {v0[0], v0[1], v1[0], v1[1]};
;                 ot[db] = att_mma<MODE>(__builtin_bit_cast(bf16x8, vw), pf, ot[db]);
;             }
;         }
; }
; template <int MODE>
; __device__ __forceinline__ void attn_phase(const Args& a, bool do_ctx, LAS unsigned char* lds, const int wid_s) {
;     ...
;             if (t + 3 < nkt) ATT_WRITEK(kK, kR, 1);
;             if (t + 2 < nkt) ATT_WRITEV(vV, 0);
;             __syncthreads();
.Latt_wskip_oB2:
	s_waitcnt vmcnt(0)
	ds_write2_b64 v141, v[128:129], v[130:131] offset1:2
	v_sub_f32_e32 v64, v64, v143
	v_sub_f32_e32 v65, v65, v143
	v_sub_f32_e32 v66, v66, v143
	v_sub_f32_e32 v67, v67, v143
	v_sub_f32_e32 v68, v68, v143
	v_sub_f32_e32 v69, v69, v143
	v_sub_f32_e32 v70, v70, v143
	v_sub_f32_e32 v71, v71, v143
	v_exp_f32_e32 v64, v64
	v_exp_f32_e32 v65, v65
	v_exp_f32_e32 v66, v66
	v_exp_f32_e32 v67, v67
	s_waitcnt lgkmcnt(0)
	s_barrier
	v_mfma_f32_32x32x16_bf16 v[48:63], v[152:155], v[108:111], v[48:63]
	v_exp_f32_e32 v68, v68
	v_exp_f32_e32 v69, v69
	v_exp_f32_e32 v70, v70
	v_exp_f32_e32 v71, v71
	v_mfma_f32_32x32x16_bf16 v[0:15], v[184:187], v[80:83], v[0:15]
	v_mfma_f32_32x32x16_bf16 v[16:31], v[188:191], v[80:83], v[16:31]
	v_cvt_pk_bf16_f32 v168, v64, v65
	v_cvt_pk_bf16_f32 v169, v66, v67
	v_cvt_pk_bf16_f32 v170, v68, v69
	v_cvt_pk_bf16_f32 v171, v70, v71
	v_mfma_f32_32x32x16_bf16 v[32:47], v[226:229], v[108:111], v[32:47]
	v_pk_add_f32 v[230:231], v[230:231], v[64:65]
	v_pk_add_f32 v[230:231], v[230:231], v[66:67]
	v_pk_add_f32 v[230:231], v[230:231], v[68:69]
	v_pk_add_f32 v[230:231], v[230:231], v[70:71]
	v_mfma_f32_32x32x16_bf16 v[48:63], v[206:209], v[116:119], v[48:63]
	v_sub_f32_e32 v72, v72, v143
	v_sub_f32_e32 v73, v73, v143
	v_sub_f32_e32 v74, v74, v143
	v_sub_f32_e32 v75, v75, v143
	v_sub_f32_e32 v76, v76, v143
	v_sub_f32_e32 v77, v77, v143
	v_sub_f32_e32 v78, v78, v143
	v_sub_f32_e32 v79, v79, v143
	v_mfma_f32_32x32x16_bf16 v[32:47], v[236:239], v[116:119], v[32:47]
	v_exp_f32_e32 v72, v72
	v_exp_f32_e32 v73, v73
	v_exp_f32_e32 v74, v74
	v_exp_f32_e32 v75, v75
	v_mfma_f32_32x32x16_bf16 v[0:15], v[192:195], v[168:171], v[0:15]
	v_exp_f32_e32 v76, v76
	v_exp_f32_e32 v77, v77
	v_exp_f32_e32 v78, v78
	v_exp_f32_e32 v79, v79
	v_mfma_f32_32x32x16_bf16 v[16:31], v[196:199], v[168:171], v[16:31]
	v_cvt_pk_bf16_f32 v80, v72, v73
	v_cvt_pk_bf16_f32 v81, v74, v75
	v_cvt_pk_bf16_f32 v82, v76, v77
	v_cvt_pk_bf16_f32 v83, v78, v79
	v_pk_add_f32 v[230:231], v[230:231], v[72:73]
	v_pk_add_f32 v[230:231], v[230:231], v[74:75]
	v_pk_add_f32 v[230:231], v[230:231], v[76:77]
	v_pk_add_f32 v[230:231], v[230:231], v[78:79]
	v_add_f32_e32 v230, v230, v231
	v_add_f32_e32 v167, v167, v230
	v_mfma_f32_32x32x16_bf16 v[0:15], v[172:175], v[80:83], v[0:15]
	v_mfma_f32_32x32x16_bf16 v[16:31], a[0:3], v[80:83], v[16:31]
	s_branch .Latt_oB_nors_join
